# T10 LDS transpose read: attention V tiles staged row-major (2 ds_write_b128 instead of 16 conflicting ds_write_b16) and consumed with ds_read_b64_tr_b16
# speedup vs baseline: 1.0113x; 1.0113x over previous
.LBB0_239:
	s_barrier
	ds_write_b128 v104, v[44:47]
	ds_write_b128 v106, v[40:43]
	v_and_b32_e32 v223, 0xff, v160
	v_lshrrev_b32_e32 v224, 2, v223
	v_and_b32_e32 v225, 3, v223
	v_lshrrev_b32_e32 v226, 1, v225
	v_bfe_u32 v227, v224, 1, 1
	v_xor_b32_e32 v226, v226, v227
	v_lshlrev_b32_e32 v226, 6, v226
	v_and_b32_e32 v225, 1, v225
	v_lshl_or_b32 v226, v225, 5, v226
	v_lshl_add_u32 v226, v224, 7, v226
	v_add_u32_e32 v223, s78, v226
	v_and_b32_e32 v226, 63, v160
	v_lshrrev_b32_e32 v224, 5, v226
	v_bfe_u32 v227, v226, 2, 2
	v_lshl_add_u32 v224, v224, 2, v227
	v_lshlrev_b32_e32 v224, 7, v224
	v_bfe_u32 v227, v226, 3, 1
	v_lshl_or_b32 v224, v227, 6, v224
	v_bfe_u32 v227, v226, 4, 1
	v_lshl_or_b32 v224, v227, 5, v224
	v_and_b32_e32 v227, 3, v226
	v_lshl_or_b32 v224, v227, 3, v224
	v_add_u32_e32 v224, s78, v224
	v_xor_b32_e32 v225, 64, v224
	ds_write_b128 v223, v[36:39] offset:8192
	ds_write_b128 v223, v[32:35] offset:8208
	s_waitcnt lgkmcnt(0)
	s_barrier
	ds_read_b128 v[32:35], v107
	ds_read_b128 v[48:51], v107 offset:4096
	s_waitcnt lgkmcnt(1)
	v_mfma_f32_32x32x16_bf16 v[32:47], v[32:35], v[72:75], 0
	ds_read_b128 v[114:117], v108
	ds_read_b128 v[118:121], v108 offset:4096
	s_mov_b32 s6, 0x3e000000
	s_mov_b32 s1, 0xf149f2ca
	v_add_u32_e32 v135, 0x2000, v111
	s_add_i32 s5, s5, 64
	s_cmpk_lg_i32 s5, 0x100
	s_waitcnt lgkmcnt(2)
	v_mfma_f32_32x32x16_bf16 v[48:63], v[48:51], v[72:75], 0
	s_waitcnt lgkmcnt(1)
	v_mfma_f32_32x32x16_bf16 v[32:47], v[114:117], v[64:67], v[32:47]
	ds_read_b128 v[114:117], v109 offset:4096
	s_waitcnt lgkmcnt(1)
	v_mfma_f32_32x32x16_bf16 v[48:63], v[118:121], v[64:67], v[48:63]
	s_waitcnt lgkmcnt(0)
	v_mfma_f32_32x32x16_bf16 v[48:63], v[114:117], v[68:71], v[48:63]
	ds_read_b128 v[114:117], v110 offset:4096
	s_waitcnt lgkmcnt(0)
	v_mfma_f32_32x32x16_bf16 v[48:63], v[114:117], v[76:79], v[48:63]
	ds_read_b128 v[114:117], v109
	ds_read_b128 v[118:121], v110
	s_waitcnt lgkmcnt(1)
	v_mfma_f32_32x32x16_bf16 v[32:47], v[114:117], v[68:71], v[32:47]
	s_nop 7
	v_mul_f32_e64 v48, v48, s6
	v_mul_f32_e64 v49, v49, s6
	v_mul_f32_e64 v50, v50, s6
	v_mul_f32_e64 v51, v51, s6
	v_mul_f32_e64 v52, v52, s6
	v_mul_f32_e64 v53, v53, s6
	v_pk_mul_f32 v[54:55], v[54:55], s[6:7] op_sel_hi:[1,0]
	v_pk_mul_f32 v[56:57], v[56:57], s[6:7] op_sel_hi:[1,0]
	v_pk_mul_f32 v[58:59], v[58:59], s[6:7] op_sel_hi:[1,0]
	v_pk_mul_f32 v[60:61], v[60:61], s[6:7] op_sel_hi:[1,0]
	s_waitcnt lgkmcnt(0)
	v_mfma_f32_32x32x16_bf16 v[32:47], v[118:121], v[76:79], v[32:47]
	v_mul_f32_e64 v62, v62, s6
	v_mul_f32_e64 v63, v63, s6
	s_nop 9
	v_pk_mul_f32 v[114:115], v[32:33], s[6:7] op_sel_hi:[1,0]
	v_pk_mul_f32 v[34:35], v[34:35], s[6:7] op_sel_hi:[1,0]
	v_max3_f32 v32, v114, s1, v115
	v_pk_mul_f32 v[36:37], v[36:37], s[6:7] op_sel_hi:[1,0]
	v_max3_f32 v32, v32, v34, v35
	v_pk_mul_f32 v[38:39], v[38:39], s[6:7] op_sel_hi:[1,0]
	v_max3_f32 v32, v32, v36, v37
	v_pk_mul_f32 v[40:41], v[40:41], s[6:7] op_sel_hi:[1,0]
	v_max3_f32 v32, v32, v38, v39
	v_pk_mul_f32 v[42:43], v[42:43], s[6:7] op_sel_hi:[1,0]
	v_max3_f32 v32, v32, v40, v41
	v_pk_mul_f32 v[44:45], v[44:45], s[6:7] op_sel_hi:[1,0]
	v_max3_f32 v32, v32, v42, v43
	v_pk_mul_f32 v[46:47], v[46:47], s[6:7] op_sel_hi:[1,0]
	v_max3_f32 v32, v32, v44, v45
	v_max3_f32 v32, v32, v46, v47
	v_max3_f32 v32, v32, v48, v49
	v_max3_f32 v32, v32, v50, v51
	v_max3_f32 v32, v32, v52, v53
	v_max3_f32 v32, v32, v54, v55
	v_max3_f32 v32, v32, v56, v57
	v_max3_f32 v32, v32, v58, v59
	v_max3_f32 v32, v32, v60, v61
	v_max3_f32 v32, v32, v62, v63
	ds_bpermute_b32 v33, v100, v32
	v_cmp_lt_f32_e32 vcc, s86, v115
	s_waitcnt lgkmcnt(0)
	v_max3_f32 v33, v112, v32, v33
	v_sub_f32_e32 v113, v115, v33
	v_sub_f32_e32 v32, v112, v33
	v_sub_f32_e32 v112, v114, v33
	v_mul_f32_e32 v113, 0x3fb8aa3b, v113
	v_exp_f32_e32 v113, v113
	v_mul_f32_e32 v112, 0x3fb8aa3b, v112
	v_sub_f32_e32 v116, v35, v33
	v_exp_f32_e32 v112, v112
	v_sub_f32_e32 v115, v34, v33
	v_mul_f32_e32 v116, 0x3fb8aa3b, v116
	v_exp_f32_e32 v116, v116
	v_mul_f32_e32 v115, 0x3fb8aa3b, v115
	v_exp_f32_e32 v115, v115
	v_cndmask_b32_e32 v113, 0, v113, vcc
	v_cmp_lt_f32_e32 vcc, s86, v114
	v_mul_f32_e32 v32, 0x3fb8aa3b, v32
	v_exp_f32_e32 v32, v32
	v_cndmask_b32_e32 v112, 0, v112, vcc
	v_cmp_lt_f32_e32 vcc, s86, v35
	v_add_f32_e32 v114, 0, v112
	v_add_f32_e32 v114, v113, v114
	v_cndmask_b32_e32 v116, 0, v116, vcc
	v_cmp_lt_f32_e32 vcc, s86, v34
	v_sub_f32_e32 v35, v36, v33
	v_mul_f32_e32 v35, 0x3fb8aa3b, v35
	v_cndmask_b32_e32 v115, 0, v115, vcc
	v_add_f32_e32 v34, v115, v114
	v_sub_f32_e32 v114, v37, v33
	v_mul_f32_e32 v114, 0x3fb8aa3b, v114
	v_exp_f32_e32 v114, v114
	v_exp_f32_e32 v35, v35
	v_cmp_lt_f32_e32 vcc, s86, v37
	v_add_f32_e32 v34, v116, v34
	v_pk_mul_f32 v[30:31], v[30:31], v[32:33] op_sel_hi:[1,0]
	v_cndmask_b32_e32 v114, 0, v114, vcc
	v_cmp_lt_f32_e32 vcc, s86, v36
	v_sub_f32_e32 v36, v39, v33
	v_mul_f32_e32 v36, 0x3fb8aa3b, v36
	v_cndmask_b32_e32 v117, 0, v35, vcc
	v_sub_f32_e32 v35, v38, v33
	v_exp_f32_e32 v36, v36
	v_mul_f32_e32 v35, 0x3fb8aa3b, v35
	v_exp_f32_e32 v35, v35
	v_cmp_lt_f32_e32 vcc, s86, v39
	v_add_f32_e32 v34, v117, v34
	v_add_f32_e32 v34, v114, v34
	v_cndmask_b32_e32 v118, 0, v36, vcc
	v_cmp_lt_f32_e32 vcc, s86, v38
	v_sub_f32_e32 v36, v41, v33
	v_mul_f32_e32 v36, 0x3fb8aa3b, v36
	v_cndmask_b32_e32 v119, 0, v35, vcc
	v_sub_f32_e32 v35, v40, v33
	v_exp_f32_e32 v36, v36
	v_mul_f32_e32 v35, 0x3fb8aa3b, v35
	v_exp_f32_e32 v35, v35
	v_cmp_lt_f32_e32 vcc, s86, v41
	v_add_f32_e32 v34, v119, v34
	v_add_f32_e32 v34, v118, v34
	v_cndmask_b32_e32 v120, 0, v36, vcc
	v_cmp_lt_f32_e32 vcc, s86, v40
	v_sub_f32_e32 v36, v43, v33
	v_mul_f32_e32 v36, 0x3fb8aa3b, v36
	v_cndmask_b32_e32 v121, 0, v35, vcc
	v_sub_f32_e32 v35, v42, v33
	v_exp_f32_e32 v36, v36
	v_mul_f32_e32 v35, 0x3fb8aa3b, v35
	v_exp_f32_e32 v35, v35
	v_cmp_lt_f32_e32 vcc, s86, v43
	v_add_f32_e32 v34, v121, v34
	v_add_f32_e32 v34, v120, v34
	v_cndmask_b32_e32 v122, 0, v36, vcc
	v_cmp_lt_f32_e32 vcc, s86, v42
	v_sub_f32_e32 v36, v45, v33
	v_mul_f32_e32 v36, 0x3fb8aa3b, v36
	v_cndmask_b32_e32 v123, 0, v35, vcc
	v_sub_f32_e32 v35, v44, v33
	v_exp_f32_e32 v36, v36
	v_mul_f32_e32 v35, 0x3fb8aa3b, v35
	v_exp_f32_e32 v35, v35
	v_cmp_lt_f32_e32 vcc, s86, v45
	v_add_f32_e32 v34, v123, v34
	v_add_f32_e32 v34, v122, v34
	v_cndmask_b32_e32 v124, 0, v36, vcc
	v_cmp_lt_f32_e32 vcc, s86, v44
	v_sub_f32_e32 v36, v47, v33
	v_mul_f32_e32 v36, 0x3fb8aa3b, v36
	v_cndmask_b32_e32 v125, 0, v35, vcc
	v_sub_f32_e32 v35, v46, v33
	v_exp_f32_e32 v36, v36
	v_mul_f32_e32 v35, 0x3fb8aa3b, v35
	v_exp_f32_e32 v35, v35
	v_cmp_lt_f32_e32 vcc, s86, v47
	v_add_f32_e32 v34, v125, v34
	v_add_f32_e32 v34, v124, v34
	v_cndmask_b32_e32 v47, 0, v36, vcc
	v_cmp_lt_f32_e32 vcc, s86, v46
	v_sub_f32_e32 v36, v49, v33
	v_mul_f32_e32 v36, 0x3fb8aa3b, v36
	v_cndmask_b32_e32 v46, 0, v35, vcc
	v_sub_f32_e32 v35, v48, v33
	v_exp_f32_e32 v36, v36
	v_mul_f32_e32 v35, 0x3fb8aa3b, v35
	v_exp_f32_e32 v35, v35
	v_cmp_lt_f32_e32 vcc, s86, v49
	v_add_f32_e32 v34, v46, v34
	v_add_f32_e32 v34, v47, v34
	v_cndmask_b32_e32 v49, 0, v36, vcc
	v_cmp_lt_f32_e32 vcc, s86, v48
	v_sub_f32_e32 v36, v51, v33
	v_mul_f32_e32 v36, 0x3fb8aa3b, v36
	v_cndmask_b32_e32 v48, 0, v35, vcc
	v_sub_f32_e32 v35, v50, v33
	v_exp_f32_e32 v36, v36
	v_mul_f32_e32 v35, 0x3fb8aa3b, v35
	v_exp_f32_e32 v35, v35
	v_cmp_lt_f32_e32 vcc, s86, v51
	v_add_f32_e32 v34, v48, v34
	v_add_f32_e32 v34, v49, v34
	v_cndmask_b32_e32 v51, 0, v36, vcc
	v_cmp_lt_f32_e32 vcc, s86, v50
	v_sub_f32_e32 v36, v53, v33
	v_mul_f32_e32 v36, 0x3fb8aa3b, v36
	v_cndmask_b32_e32 v50, 0, v35, vcc
	v_sub_f32_e32 v35, v52, v33
	v_exp_f32_e32 v36, v36
	v_mul_f32_e32 v35, 0x3fb8aa3b, v35
	v_exp_f32_e32 v35, v35
	v_cmp_lt_f32_e32 vcc, s86, v53
	v_add_f32_e32 v34, v50, v34
	v_add_f32_e32 v34, v51, v34
	v_cndmask_b32_e32 v53, 0, v36, vcc
	v_cmp_lt_f32_e32 vcc, s86, v52
	v_sub_f32_e32 v36, v55, v33
	v_mul_f32_e32 v36, 0x3fb8aa3b, v36
	v_cndmask_b32_e32 v52, 0, v35, vcc
	v_sub_f32_e32 v35, v54, v33
	v_exp_f32_e32 v36, v36
	v_mul_f32_e32 v35, 0x3fb8aa3b, v35
	v_exp_f32_e32 v35, v35
	v_cmp_lt_f32_e32 vcc, s86, v55
	v_add_f32_e32 v34, v52, v34
	v_add_f32_e32 v34, v53, v34
	v_cndmask_b32_e32 v55, 0, v36, vcc
	v_cmp_lt_f32_e32 vcc, s86, v54
	v_sub_f32_e32 v36, v57, v33
	v_mul_f32_e32 v36, 0x3fb8aa3b, v36
	v_cndmask_b32_e32 v54, 0, v35, vcc
	v_sub_f32_e32 v35, v56, v33
	v_exp_f32_e32 v36, v36
	v_mul_f32_e32 v35, 0x3fb8aa3b, v35
	v_exp_f32_e32 v35, v35
	v_cmp_lt_f32_e32 vcc, s86, v57
	v_add_f32_e32 v34, v54, v34
	v_add_f32_e32 v34, v55, v34
	v_cndmask_b32_e32 v57, 0, v36, vcc
	v_cmp_lt_f32_e32 vcc, s86, v56
	v_sub_f32_e32 v36, v59, v33
	v_mul_f32_e32 v36, 0x3fb8aa3b, v36
	v_cndmask_b32_e32 v56, 0, v35, vcc
	v_sub_f32_e32 v35, v58, v33
	v_exp_f32_e32 v36, v36
	v_mul_f32_e32 v35, 0x3fb8aa3b, v35
	v_exp_f32_e32 v35, v35
	v_cmp_lt_f32_e32 vcc, s86, v59
	v_add_f32_e32 v34, v56, v34
	v_add_f32_e32 v34, v57, v34
	v_cndmask_b32_e32 v59, 0, v36, vcc
	v_cmp_lt_f32_e32 vcc, s86, v58
	v_cvt_pk_bf16_f32 v38, v112, v113
	v_add_u32_e32 v112, 0x3000, v111
	v_cndmask_b32_e32 v58, 0, v35, vcc
	v_add_f32_e32 v34, v58, v34
	v_add_f32_e32 v126, v59, v34
	v_sub_f32_e32 v34, v60, v33
	v_mul_f32_e32 v127, 0x3fb8aa3b, v34
	ds_read_b64_tr_b16 v[34:35], v224 offset:8192
	ds_read_b64_tr_b16 v[36:37], v224 offset:9216
	ds_read_b64_tr_b16 v[42:43], v225 offset:8192
	ds_read_b64_tr_b16 v[44:45], v225 offset:9216
	v_pk_mul_f32 v[28:29], v[28:29], v[32:33] op_sel_hi:[1,0]
	v_pk_mul_f32 v[26:27], v[26:27], v[32:33] op_sel_hi:[1,0]
	v_pk_mul_f32 v[24:25], v[24:25], v[32:33] op_sel_hi:[1,0]
	v_pk_mul_f32 v[22:23], v[22:23], v[32:33] op_sel_hi:[1,0]
	v_pk_mul_f32 v[20:21], v[20:21], v[32:33] op_sel_hi:[1,0]
	v_pk_mul_f32 v[18:19], v[18:19], v[32:33] op_sel_hi:[1,0]
	v_pk_mul_f32 v[16:17], v[16:17], v[32:33] op_sel_hi:[1,0]
	v_cvt_pk_bf16_f32 v39, v115, v116
	v_cvt_pk_bf16_f32 v40, v117, v114
	v_cvt_pk_bf16_f32 v41, v119, v118
	v_sub_f32_e32 v134, v61, v33
	v_pk_mul_f32 v[14:15], v[14:15], v[32:33] op_sel_hi:[1,0]
	s_waitcnt lgkmcnt(2)
	v_mfma_f32_32x32x16_bf16 v[16:31], v[34:37], v[38:41], v[16:31]
	ds_read_b64_tr_b16 v[34:35], v224 offset:10240
	ds_read_b64_tr_b16 v[36:37], v224 offset:11264
	v_mul_f32_e64 v12, v12, v32
	v_mul_f32_e64 v13, v13, v32
	v_mul_f32_e64 v10, v10, v32
	v_mul_f32_e64 v11, v11, v32
	v_pk_mul_f32 v[8:9], v[8:9], v[32:33] op_sel_hi:[1,0]
	v_pk_mul_f32 v[6:7], v[6:7], v[32:33] op_sel_hi:[1,0]
	v_pk_mul_f32 v[4:5], v[4:5], v[32:33] op_sel_hi:[1,0]
	v_pk_mul_f32 v[2:3], v[2:3], v[32:33] op_sel_hi:[1,0]
	v_pk_mul_f32 v[0:1], v[0:1], v[32:33] op_sel_hi:[1,0]
	v_cmp_lt_f32_e32 vcc, s86, v61
	v_sub_f32_e32 v61, v62, v33
	s_waitcnt lgkmcnt(2)
	v_mfma_f32_32x32x16_bf16 v[0:15], v[42:45], v[38:41], v[0:15]
	v_mul_f32_e32 v38, 0x3fb8aa3b, v134
	v_exp_f32_e32 v113, v38
	v_cvt_pk_bf16_f32 v38, v121, v120
	v_cvt_pk_bf16_f32 v39, v123, v122
	v_cvt_pk_bf16_f32 v40, v125, v124
	v_cvt_pk_bf16_f32 v41, v46, v47
	ds_read_b64_tr_b16 v[42:43], v225 offset:10240
	ds_read_b64_tr_b16 v[44:45], v225 offset:11264
	v_cndmask_b32_e32 v46, 0, v113, vcc
	s_waitcnt lgkmcnt(2)
	v_mfma_f32_32x32x16_bf16 v[16:31], v[34:37], v[38:41], v[16:31]
	v_exp_f32_e32 v34, v127
	v_cmp_lt_f32_e32 vcc, s86, v60
	s_nop 1
	v_cndmask_b32_e32 v47, 0, v34, vcc
	ds_read_b64_tr_b16 v[34:35], v224 offset:12288
	ds_read_b64_tr_b16 v[36:37], v224 offset:13312
	v_cmp_lt_f32_e32 vcc, s86, v63
	s_waitcnt lgkmcnt(2)
	v_mfma_f32_32x32x16_bf16 v[0:15], v[42:45], v[38:41], v[0:15]
	ds_read_b64_tr_b16 v[42:43], v225 offset:12288
	ds_read_b64_tr_b16 v[44:45], v225 offset:13312
	v_cvt_pk_bf16_f32 v38, v48, v49
	v_cvt_pk_bf16_f32 v39, v50, v51
	v_cvt_pk_bf16_f32 v40, v52, v53
	v_cvt_pk_bf16_f32 v41, v54, v55
	v_add_f32_e32 v60, v47, v126
	v_add_f32_e32 v60, v46, v60
	s_waitcnt lgkmcnt(2)
	v_mfma_f32_32x32x16_bf16 v[16:31], v[34:37], v[38:41], v[16:31]
	v_sub_f32_e32 v34, v63, v33
	v_mul_f32_e32 v34, 0x3fb8aa3b, v34
	v_exp_f32_e32 v34, v34
	v_mul_f32_e32 v35, 0x3fb8aa3b, v61
	v_exp_f32_e32 v48, v35
	v_cndmask_b32_e32 v49, 0, v34, vcc
	s_waitcnt lgkmcnt(0)
	v_mfma_f32_32x32x16_bf16 v[0:15], v[42:45], v[38:41], v[0:15]
	ds_read_b64_tr_b16 v[34:35], v224 offset:14336
	ds_read_b64_tr_b16 v[36:37], v224 offset:15360
	ds_read_b64_tr_b16 v[42:43], v225 offset:14336
	ds_read_b64_tr_b16 v[44:45], v225 offset:15360
	v_cmp_lt_f32_e32 vcc, s86, v62
	v_cvt_pk_bf16_f32 v38, v56, v57
	v_cvt_pk_bf16_f32 v39, v58, v59
	v_cndmask_b32_e32 v41, 0, v48, vcc
	v_add_f32_e32 v48, v41, v60
	v_cvt_pk_bf16_f32 v40, v47, v46
	v_cvt_pk_bf16_f32 v41, v41, v49
	s_waitcnt lgkmcnt(2)
	s_nop 0
	v_mfma_f32_32x32x16_bf16 v[16:31], v[34:37], v[38:41], v[16:31]
	v_add_f32_e32 v34, v49, v48
	ds_bpermute_b32 v35, v100, v34
	s_waitcnt lgkmcnt(0)
	v_add_f32_e32 v34, v34, v35
	v_mfma_f32_32x32x16_bf16 v[0:15], v[42:45], v[38:41], v[0:15]
	v_fmac_f32_e32 v34, v105, v32
	s_cbranch_scc1 .LBB0_237
	v_max_f32_e32 v32, v99, v99
	v_max_f32_e32 v35, v33, v33
	v_max_f32_e32 v32, v35, v32
	v_sub_f32_e32 v33, v33, v32
	v_sub_f32_e32 v32, v99, v32
	v_mul_f32_e32 v33, 0x3fb8aa3b, v33
	v_mul_f32_e32 v32, 0x3fb8aa3b, v32
	v_exp_f32_e32 v33, v33
	v_exp_f32_e32 v32, v32
	s_lshl_b32 s92, s4, 1
	v_lshlrev_b32_e32 v128, 3, v98
	v_fmac_f32_e32 v32, v33, v34
	v_div_scale_f32 v34, s[0:1], v32, v32, v33
	v_rcp_f32_e32 v35, v34
	v_readlane_b32 s0, v254, 43
	v_readlane_b32 s1, v254, 44
	v_fma_f32 v36, -v34, v35, 1.0
	v_fmac_f32_e32 v35, v36, v35
	v_div_scale_f32 v36, vcc, v33, v32, v33
	v_mul_f32_e32 v37, v36, v35
	v_fma_f32 v38, -v34, v37, v36
	v_fmac_f32_e32 v37, v38, v35
	v_fma_f32 v34, -v34, v37, v36
	v_div_fmas_f32 v34, v34, v35, v37
	v_div_fixup_f32 v32, v34, v32, v33
	v_lshlrev_b64 v[34:35], 11, v[96:97]
	v_lshl_add_u64 v[34:35], s[0:1], 0, v[34:35]
	v_lshl_add_u64 v[34:35], v[34:35], 0, s[92:93]
	v_pk_mul_f32 v[16:17], v[16:17], v[32:33] op_sel_hi:[1,0]
	v_pk_mul_f32 v[18:19], v[18:19], v[32:33] op_sel_hi:[1,0]
	v_cvt_pk_bf16_f32 v16, v16, v17
	v_cvt_pk_bf16_f32 v17, v18, v19
	v_lshl_add_u64 v[18:19], v[34:35], 0, v[128:129]
	s_mov_b64 s[0:1], 0x153ca600
	v_lshl_add_u64 v[34:35], v[18:19], 0, s[0:1]
	s_mov_b32 s0, 0x153ca000
	v_add_co_u32_e32 v18, vcc, s0, v18
	v_pk_mul_f32 v[0:1], v[0:1], v[32:33] op_sel_hi:[1,0]
	v_pk_mul_f32 v[2:3], v[2:3], v[32:33] op_sel_hi:[1,0]
	v_addc_co_u32_e32 v19, vcc, 0, v19, vcc
	v_cvt_pk_bf16_f32 v0, v0, v1
	v_cvt_pk_bf16_f32 v1, v2, v3
	global_store_dwordx2 v[18:19], v[16:17], off offset:1536
	v_pk_mul_f32 v[16:17], v[20:21], v[32:33] op_sel_hi:[1,0]
	v_pk_mul_f32 v[18:19], v[22:23], v[32:33] op_sel_hi:[1,0]
	global_store_dwordx2 v[34:35], v[0:1], off offset:64
	v_pk_mul_f32 v[0:1], v[4:5], v[32:33] op_sel_hi:[1,0]
	v_pk_mul_f32 v[2:3], v[6:7], v[32:33] op_sel_hi:[1,0]
	v_cvt_pk_bf16_f32 v16, v16, v17
	v_cvt_pk_bf16_f32 v17, v18, v19
	v_cvt_pk_bf16_f32 v0, v0, v1
	v_cvt_pk_bf16_f32 v1, v2, v3
	global_store_dwordx2 v[34:35], v[16:17], off offset:16
	v_pk_mul_f32 v[16:17], v[24:25], v[32:33] op_sel_hi:[1,0]
	v_pk_mul_f32 v[18:19], v[26:27], v[32:33] op_sel_hi:[1,0]
	global_store_dwordx2 v[34:35], v[0:1], off offset:80
	v_pk_mul_f32 v[0:1], v[8:9], v[32:33] op_sel_hi:[1,0]
	v_pk_mul_f32 v[2:3], v[10:11], v[32:33] op_sel_hi:[1,0]
	v_cvt_pk_bf16_f32 v16, v16, v17
	v_cvt_pk_bf16_f32 v17, v18, v19
	v_cvt_pk_bf16_f32 v0, v0, v1
	v_cvt_pk_bf16_f32 v1, v2, v3
	global_store_dwordx2 v[34:35], v[16:17], off offset:32
	v_pk_mul_f32 v[16:17], v[28:29], v[32:33] op_sel_hi:[1,0]
	v_pk_mul_f32 v[18:19], v[30:31], v[32:33] op_sel_hi:[1,0]
	global_store_dwordx2 v[34:35], v[0:1], off offset:96
	v_pk_mul_f32 v[0:1], v[12:13], v[32:33] op_sel_hi:[1,0]
	v_pk_mul_f32 v[2:3], v[14:15], v[32:33] op_sel_hi:[1,0]
	v_cvt_pk_bf16_f32 v16, v16, v17
	v_cvt_pk_bf16_f32 v17, v18, v19
	v_cvt_pk_bf16_f32 v0, v0, v1
	v_cvt_pk_bf16_f32 v1, v2, v3
	global_store_dwordx2 v[34:35], v[16:17], off offset:48
	global_store_dwordx2 v[34:35], v[0:1], off offset:112
	s_barrier
	s_mov_b64 s[0:1], 0

.LBB0_245:
	s_barrier
	ds_write_b128 v104, v[44:47]
	ds_write_b128 v105, v[40:43]
	v_and_b32_e32 v223, 0xff, v160
	v_lshrrev_b32_e32 v224, 2, v223
	v_and_b32_e32 v225, 3, v223
	v_lshrrev_b32_e32 v226, 1, v225
	v_bfe_u32 v227, v224, 1, 1
	v_xor_b32_e32 v226, v226, v227
	v_lshlrev_b32_e32 v226, 6, v226
	v_and_b32_e32 v225, 1, v225
	v_lshl_or_b32 v226, v225, 5, v226
	v_lshl_add_u32 v226, v224, 7, v226
	v_add_u32_e32 v223, s78, v226
	v_and_b32_e32 v226, 63, v160
	v_lshrrev_b32_e32 v224, 5, v226
	v_bfe_u32 v227, v226, 2, 2
	v_lshl_add_u32 v224, v224, 2, v227
	v_lshlrev_b32_e32 v224, 7, v224
	v_bfe_u32 v227, v226, 3, 1
	v_lshl_or_b32 v224, v227, 6, v224
	v_bfe_u32 v227, v226, 4, 1
	v_lshl_or_b32 v224, v227, 5, v224
	v_and_b32_e32 v227, 3, v226
	v_lshl_or_b32 v224, v227, 3, v224
	v_add_u32_e32 v224, s78, v224
	v_xor_b32_e32 v225, 64, v224
	ds_write_b128 v223, v[36:39] offset:8192
	ds_write_b128 v223, v[32:35] offset:8208
	s_waitcnt lgkmcnt(0)
	s_barrier
	ds_read_b128 v[32:35], v106
	ds_read_b128 v[48:51], v106 offset:4096
	s_waitcnt lgkmcnt(1)
	v_mfma_f32_32x32x16_bf16 v[32:47], v[32:35], v[64:67], 0
	ds_read_b128 v[114:117], v108
	ds_read_b128 v[118:121], v108 offset:4096
	s_mov_b32 s6, 0x3e000000
	s_mov_b32 s5, 0xf149f2ca
	v_add_u32_e32 v134, 0x2000, v111
	s_add_u32 s0, s0, 0x74000
	s_addc_u32 s1, s1, 0
	s_cmp_lg_u32 s0, 0x1d0000
	s_waitcnt lgkmcnt(2)
	v_mfma_f32_32x32x16_bf16 v[48:63], v[48:51], v[64:67], 0
	s_waitcnt lgkmcnt(1)
	v_mfma_f32_32x32x16_bf16 v[32:47], v[114:117], v[68:71], v[32:47]
	ds_read_b128 v[114:117], v109 offset:4096
	s_waitcnt lgkmcnt(1)
	v_mfma_f32_32x32x16_bf16 v[48:63], v[118:121], v[68:71], v[48:63]
	s_waitcnt lgkmcnt(0)
	v_mfma_f32_32x32x16_bf16 v[48:63], v[114:117], v[72:75], v[48:63]
	ds_read_b128 v[114:117], v110 offset:4096
	s_waitcnt lgkmcnt(0)
	v_mfma_f32_32x32x16_bf16 v[48:63], v[114:117], v[76:79], v[48:63]
	ds_read_b128 v[114:117], v109
	ds_read_b128 v[118:121], v110
	s_waitcnt lgkmcnt(1)
	v_mfma_f32_32x32x16_bf16 v[32:47], v[114:117], v[72:75], v[32:47]
	s_nop 7
	v_mul_f32_e64 v48, v48, s6
	v_mul_f32_e64 v49, v49, s6
	v_mul_f32_e64 v50, v50, s6
	v_mul_f32_e64 v51, v51, s6
	v_mul_f32_e64 v52, v52, s6
	v_mul_f32_e64 v53, v53, s6
	v_pk_mul_f32 v[54:55], v[54:55], s[6:7] op_sel_hi:[1,0]
	v_pk_mul_f32 v[56:57], v[56:57], s[6:7] op_sel_hi:[1,0]
	v_pk_mul_f32 v[58:59], v[58:59], s[6:7] op_sel_hi:[1,0]
	v_pk_mul_f32 v[60:61], v[60:61], s[6:7] op_sel_hi:[1,0]
	s_waitcnt lgkmcnt(0)
	v_mfma_f32_32x32x16_bf16 v[32:47], v[118:121], v[76:79], v[32:47]
	v_mul_f32_e64 v62, v62, s6
	v_mul_f32_e64 v63, v63, s6
	s_nop 9
	v_pk_mul_f32 v[114:115], v[32:33], s[6:7] op_sel_hi:[1,0]
	v_pk_mul_f32 v[34:35], v[34:35], s[6:7] op_sel_hi:[1,0]
	v_max3_f32 v32, v114, s5, v115
	v_pk_mul_f32 v[36:37], v[36:37], s[6:7] op_sel_hi:[1,0]
	v_max3_f32 v32, v32, v34, v35
	v_pk_mul_f32 v[38:39], v[38:39], s[6:7] op_sel_hi:[1,0]
	v_max3_f32 v32, v32, v36, v37
	v_pk_mul_f32 v[40:41], v[40:41], s[6:7] op_sel_hi:[1,0]
	v_max3_f32 v32, v32, v38, v39
	v_pk_mul_f32 v[42:43], v[42:43], s[6:7] op_sel_hi:[1,0]
	v_max3_f32 v32, v32, v40, v41
	v_pk_mul_f32 v[44:45], v[44:45], s[6:7] op_sel_hi:[1,0]
	v_max3_f32 v32, v32, v42, v43
	v_pk_mul_f32 v[46:47], v[46:47], s[6:7] op_sel_hi:[1,0]
	v_max3_f32 v32, v32, v44, v45
	v_max3_f32 v32, v32, v46, v47
	v_max3_f32 v32, v32, v48, v49
	v_max3_f32 v32, v32, v50, v51
	v_max3_f32 v32, v32, v52, v53
	v_max3_f32 v32, v32, v54, v55
	v_max3_f32 v32, v32, v56, v57
	v_max3_f32 v32, v32, v58, v59
	v_max3_f32 v32, v32, v60, v61
	v_max3_f32 v32, v32, v62, v63
	ds_bpermute_b32 v33, v101, v32
	v_cmp_lt_f32_e32 vcc, s86, v115
	s_waitcnt lgkmcnt(0)
	v_max3_f32 v33, v112, v32, v33
	v_sub_f32_e32 v113, v115, v33
	v_sub_f32_e32 v32, v112, v33
	v_sub_f32_e32 v112, v114, v33
	v_mul_f32_e32 v113, 0x3fb8aa3b, v113
	v_exp_f32_e32 v113, v113
	v_mul_f32_e32 v112, 0x3fb8aa3b, v112
	v_sub_f32_e32 v116, v35, v33
	v_exp_f32_e32 v112, v112
	v_sub_f32_e32 v115, v34, v33
	v_mul_f32_e32 v116, 0x3fb8aa3b, v116
	v_exp_f32_e32 v116, v116
	v_mul_f32_e32 v115, 0x3fb8aa3b, v115
	v_exp_f32_e32 v115, v115
	v_cndmask_b32_e32 v113, 0, v113, vcc
	v_cmp_lt_f32_e32 vcc, s86, v114
	v_mul_f32_e32 v32, 0x3fb8aa3b, v32
	v_exp_f32_e32 v32, v32
	v_cndmask_b32_e32 v112, 0, v112, vcc
	v_cmp_lt_f32_e32 vcc, s86, v35
	v_add_f32_e32 v114, 0, v112
	v_add_f32_e32 v114, v113, v114
	v_cndmask_b32_e32 v116, 0, v116, vcc
	v_cmp_lt_f32_e32 vcc, s86, v34
	v_sub_f32_e32 v35, v36, v33
	v_mul_f32_e32 v35, 0x3fb8aa3b, v35
	v_cndmask_b32_e32 v115, 0, v115, vcc
	v_add_f32_e32 v34, v115, v114
	v_sub_f32_e32 v114, v37, v33
	v_mul_f32_e32 v114, 0x3fb8aa3b, v114
	v_exp_f32_e32 v114, v114
	v_exp_f32_e32 v35, v35
	v_cmp_lt_f32_e32 vcc, s86, v37
	v_add_f32_e32 v34, v116, v34
	v_pk_mul_f32 v[30:31], v[30:31], v[32:33] op_sel_hi:[1,0]
	v_cndmask_b32_e32 v114, 0, v114, vcc
	v_cmp_lt_f32_e32 vcc, s86, v36
	v_sub_f32_e32 v36, v39, v33
	v_mul_f32_e32 v36, 0x3fb8aa3b, v36
	v_cndmask_b32_e32 v117, 0, v35, vcc
	v_sub_f32_e32 v35, v38, v33
	v_exp_f32_e32 v36, v36
	v_mul_f32_e32 v35, 0x3fb8aa3b, v35
	v_exp_f32_e32 v35, v35
	v_cmp_lt_f32_e32 vcc, s86, v39
	v_add_f32_e32 v34, v117, v34
	v_add_f32_e32 v34, v114, v34
	v_cndmask_b32_e32 v118, 0, v36, vcc
	v_cmp_lt_f32_e32 vcc, s86, v38
	v_sub_f32_e32 v36, v41, v33
	v_mul_f32_e32 v36, 0x3fb8aa3b, v36
	v_cndmask_b32_e32 v119, 0, v35, vcc
	v_sub_f32_e32 v35, v40, v33
	v_exp_f32_e32 v36, v36
	v_mul_f32_e32 v35, 0x3fb8aa3b, v35
	v_exp_f32_e32 v35, v35
	v_cmp_lt_f32_e32 vcc, s86, v41
	v_add_f32_e32 v34, v119, v34
	v_add_f32_e32 v34, v118, v34
	v_cndmask_b32_e32 v120, 0, v36, vcc
	v_cmp_lt_f32_e32 vcc, s86, v40
	v_sub_f32_e32 v36, v43, v33
	v_mul_f32_e32 v36, 0x3fb8aa3b, v36
	v_cndmask_b32_e32 v121, 0, v35, vcc
	v_sub_f32_e32 v35, v42, v33
	v_exp_f32_e32 v36, v36
	v_mul_f32_e32 v35, 0x3fb8aa3b, v35
	v_exp_f32_e32 v35, v35
	v_cmp_lt_f32_e32 vcc, s86, v43
	v_add_f32_e32 v34, v121, v34
	v_add_f32_e32 v34, v120, v34
	v_cndmask_b32_e32 v122, 0, v36, vcc
	v_cmp_lt_f32_e32 vcc, s86, v42
	v_sub_f32_e32 v36, v45, v33
	v_mul_f32_e32 v36, 0x3fb8aa3b, v36
	v_cndmask_b32_e32 v123, 0, v35, vcc
	v_sub_f32_e32 v35, v44, v33
	v_exp_f32_e32 v36, v36
	v_mul_f32_e32 v35, 0x3fb8aa3b, v35
	v_exp_f32_e32 v35, v35
	v_cmp_lt_f32_e32 vcc, s86, v45
	v_add_f32_e32 v34, v123, v34
	v_add_f32_e32 v34, v122, v34
	v_cndmask_b32_e32 v124, 0, v36, vcc
	v_cmp_lt_f32_e32 vcc, s86, v44
	v_sub_f32_e32 v36, v47, v33
	v_mul_f32_e32 v36, 0x3fb8aa3b, v36
	v_cndmask_b32_e32 v125, 0, v35, vcc
	v_sub_f32_e32 v35, v46, v33
	v_exp_f32_e32 v36, v36
	v_mul_f32_e32 v35, 0x3fb8aa3b, v35
	v_exp_f32_e32 v35, v35
	v_cmp_lt_f32_e32 vcc, s86, v47
	v_add_f32_e32 v34, v125, v34
	v_add_f32_e32 v34, v124, v34
	v_cndmask_b32_e32 v47, 0, v36, vcc
	v_cmp_lt_f32_e32 vcc, s86, v46
	v_sub_f32_e32 v36, v49, v33
	v_mul_f32_e32 v36, 0x3fb8aa3b, v36
	v_cndmask_b32_e32 v46, 0, v35, vcc
	v_sub_f32_e32 v35, v48, v33
	v_exp_f32_e32 v36, v36
	v_mul_f32_e32 v35, 0x3fb8aa3b, v35
	v_exp_f32_e32 v35, v35
	v_cmp_lt_f32_e32 vcc, s86, v49
	v_add_f32_e32 v34, v46, v34
	v_add_f32_e32 v34, v47, v34
	v_cndmask_b32_e32 v49, 0, v36, vcc
	v_cmp_lt_f32_e32 vcc, s86, v48
	v_sub_f32_e32 v36, v51, v33
	v_mul_f32_e32 v36, 0x3fb8aa3b, v36
	v_cndmask_b32_e32 v48, 0, v35, vcc
	v_sub_f32_e32 v35, v50, v33
	v_exp_f32_e32 v36, v36
	v_mul_f32_e32 v35, 0x3fb8aa3b, v35
	v_exp_f32_e32 v35, v35
	v_cmp_lt_f32_e32 vcc, s86, v51
	v_add_f32_e32 v34, v48, v34
	v_add_f32_e32 v34, v49, v34
	v_cndmask_b32_e32 v51, 0, v36, vcc
	v_cmp_lt_f32_e32 vcc, s86, v50
	v_sub_f32_e32 v36, v53, v33
	v_mul_f32_e32 v36, 0x3fb8aa3b, v36
	v_cndmask_b32_e32 v50, 0, v35, vcc
	v_sub_f32_e32 v35, v52, v33
	v_exp_f32_e32 v36, v36
	v_mul_f32_e32 v35, 0x3fb8aa3b, v35
	v_exp_f32_e32 v35, v35
	v_cmp_lt_f32_e32 vcc, s86, v53
	v_add_f32_e32 v34, v50, v34
	v_add_f32_e32 v34, v51, v34
	v_cndmask_b32_e32 v53, 0, v36, vcc
	v_cmp_lt_f32_e32 vcc, s86, v52
	v_sub_f32_e32 v36, v55, v33
	v_mul_f32_e32 v36, 0x3fb8aa3b, v36
	v_cndmask_b32_e32 v52, 0, v35, vcc
	v_sub_f32_e32 v35, v54, v33
	v_exp_f32_e32 v36, v36
	v_mul_f32_e32 v35, 0x3fb8aa3b, v35
	v_exp_f32_e32 v35, v35
	v_cmp_lt_f32_e32 vcc, s86, v55
	v_add_f32_e32 v34, v52, v34
	v_add_f32_e32 v34, v53, v34
	v_cndmask_b32_e32 v55, 0, v36, vcc
	v_cmp_lt_f32_e32 vcc, s86, v54
	v_sub_f32_e32 v36, v57, v33
	v_mul_f32_e32 v36, 0x3fb8aa3b, v36
	v_cndmask_b32_e32 v54, 0, v35, vcc
	v_sub_f32_e32 v35, v56, v33
	v_exp_f32_e32 v36, v36
	v_mul_f32_e32 v35, 0x3fb8aa3b, v35
	v_exp_f32_e32 v35, v35
	v_cmp_lt_f32_e32 vcc, s86, v57
	v_add_f32_e32 v34, v54, v34
	v_add_f32_e32 v34, v55, v34
	v_cndmask_b32_e32 v57, 0, v36, vcc
	v_cmp_lt_f32_e32 vcc, s86, v56
	v_sub_f32_e32 v36, v59, v33
	v_mul_f32_e32 v36, 0x3fb8aa3b, v36
	v_cndmask_b32_e32 v56, 0, v35, vcc
	v_sub_f32_e32 v35, v58, v33
	v_exp_f32_e32 v36, v36
	v_mul_f32_e32 v35, 0x3fb8aa3b, v35
	v_exp_f32_e32 v35, v35
	v_cmp_lt_f32_e32 vcc, s86, v59
	v_add_f32_e32 v34, v56, v34
	v_add_f32_e32 v34, v57, v34
	v_cndmask_b32_e32 v59, 0, v36, vcc
	v_cmp_lt_f32_e32 vcc, s86, v58
	v_cvt_pk_bf16_f32 v38, v112, v113
	v_add_u32_e32 v112, 0x3000, v111
	v_cndmask_b32_e32 v58, 0, v35, vcc
	v_add_f32_e32 v34, v58, v34
	v_add_f32_e32 v126, v59, v34
	v_sub_f32_e32 v34, v60, v33
	v_mul_f32_e32 v127, 0x3fb8aa3b, v34
	ds_read_b64_tr_b16 v[34:35], v224 offset:8192
	ds_read_b64_tr_b16 v[36:37], v224 offset:9216
	ds_read_b64_tr_b16 v[42:43], v225 offset:8192
	ds_read_b64_tr_b16 v[44:45], v225 offset:9216
	v_pk_mul_f32 v[28:29], v[28:29], v[32:33] op_sel_hi:[1,0]
	v_pk_mul_f32 v[26:27], v[26:27], v[32:33] op_sel_hi:[1,0]
	v_pk_mul_f32 v[24:25], v[24:25], v[32:33] op_sel_hi:[1,0]
	v_pk_mul_f32 v[22:23], v[22:23], v[32:33] op_sel_hi:[1,0]
	v_pk_mul_f32 v[20:21], v[20:21], v[32:33] op_sel_hi:[1,0]
	v_pk_mul_f32 v[18:19], v[18:19], v[32:33] op_sel_hi:[1,0]
	v_pk_mul_f32 v[16:17], v[16:17], v[32:33] op_sel_hi:[1,0]
	v_cvt_pk_bf16_f32 v39, v115, v116
	v_cvt_pk_bf16_f32 v40, v117, v114
	v_cvt_pk_bf16_f32 v41, v119, v118
	v_sub_f32_e32 v128, v61, v33
	v_pk_mul_f32 v[14:15], v[14:15], v[32:33] op_sel_hi:[1,0]
	s_waitcnt lgkmcnt(2)
	v_mfma_f32_32x32x16_bf16 v[16:31], v[34:37], v[38:41], v[16:31]
	ds_read_b64_tr_b16 v[34:35], v224 offset:10240
	ds_read_b64_tr_b16 v[36:37], v224 offset:11264
	v_mul_f32_e64 v12, v12, v32
	v_mul_f32_e64 v13, v13, v32
	v_mul_f32_e64 v10, v10, v32
	v_mul_f32_e64 v11, v11, v32
	v_pk_mul_f32 v[8:9], v[8:9], v[32:33] op_sel_hi:[1,0]
	v_pk_mul_f32 v[6:7], v[6:7], v[32:33] op_sel_hi:[1,0]
	v_pk_mul_f32 v[4:5], v[4:5], v[32:33] op_sel_hi:[1,0]
	v_pk_mul_f32 v[2:3], v[2:3], v[32:33] op_sel_hi:[1,0]
	v_pk_mul_f32 v[0:1], v[0:1], v[32:33] op_sel_hi:[1,0]
	v_cmp_lt_f32_e32 vcc, s86, v61
	v_sub_f32_e32 v61, v62, v33
	s_waitcnt lgkmcnt(2)
	v_mfma_f32_32x32x16_bf16 v[0:15], v[42:45], v[38:41], v[0:15]
	v_mul_f32_e32 v38, 0x3fb8aa3b, v128
	v_exp_f32_e32 v113, v38
	v_cvt_pk_bf16_f32 v38, v121, v120
	v_cvt_pk_bf16_f32 v39, v123, v122
	v_cvt_pk_bf16_f32 v40, v125, v124
	v_cvt_pk_bf16_f32 v41, v46, v47
	ds_read_b64_tr_b16 v[42:43], v225 offset:10240
	ds_read_b64_tr_b16 v[44:45], v225 offset:11264
	v_cndmask_b32_e32 v46, 0, v113, vcc
	s_waitcnt lgkmcnt(2)
	v_mfma_f32_32x32x16_bf16 v[16:31], v[34:37], v[38:41], v[16:31]
	v_exp_f32_e32 v34, v127
	v_cmp_lt_f32_e32 vcc, s86, v60
	s_nop 1
	v_cndmask_b32_e32 v47, 0, v34, vcc
	ds_read_b64_tr_b16 v[34:35], v224 offset:12288
	ds_read_b64_tr_b16 v[36:37], v224 offset:13312
	v_cmp_lt_f32_e32 vcc, s86, v63
	s_waitcnt lgkmcnt(2)
	v_mfma_f32_32x32x16_bf16 v[0:15], v[42:45], v[38:41], v[0:15]
	ds_read_b64_tr_b16 v[42:43], v225 offset:12288
	ds_read_b64_tr_b16 v[44:45], v225 offset:13312
	v_cvt_pk_bf16_f32 v38, v48, v49
	v_cvt_pk_bf16_f32 v39, v50, v51
	v_cvt_pk_bf16_f32 v40, v52, v53
	v_cvt_pk_bf16_f32 v41, v54, v55
	v_add_f32_e32 v60, v47, v126
	v_add_f32_e32 v60, v46, v60
	s_waitcnt lgkmcnt(2)
	v_mfma_f32_32x32x16_bf16 v[16:31], v[34:37], v[38:41], v[16:31]
	v_sub_f32_e32 v34, v63, v33
	v_mul_f32_e32 v34, 0x3fb8aa3b, v34
	v_exp_f32_e32 v34, v34
	v_mul_f32_e32 v35, 0x3fb8aa3b, v61
	v_exp_f32_e32 v48, v35
	v_cndmask_b32_e32 v49, 0, v34, vcc
	s_waitcnt lgkmcnt(0)
	v_mfma_f32_32x32x16_bf16 v[0:15], v[42:45], v[38:41], v[0:15]
	ds_read_b64_tr_b16 v[34:35], v224 offset:14336
	ds_read_b64_tr_b16 v[36:37], v224 offset:15360
	ds_read_b64_tr_b16 v[42:43], v225 offset:14336
	ds_read_b64_tr_b16 v[44:45], v225 offset:15360
	v_cmp_lt_f32_e32 vcc, s86, v62
	v_cvt_pk_bf16_f32 v38, v56, v57
	v_cvt_pk_bf16_f32 v39, v58, v59
	v_cndmask_b32_e32 v41, 0, v48, vcc
	v_add_f32_e32 v48, v41, v60
	v_cvt_pk_bf16_f32 v40, v47, v46
	v_cvt_pk_bf16_f32 v41, v41, v49
	s_waitcnt lgkmcnt(2)
	s_nop 0
	v_mfma_f32_32x32x16_bf16 v[16:31], v[34:37], v[38:41], v[16:31]
	v_add_f32_e32 v34, v49, v48
	ds_bpermute_b32 v35, v101, v34
	s_waitcnt lgkmcnt(0)
	v_add_f32_e32 v34, v34, v35
	v_mfma_f32_32x32x16_bf16 v[0:15], v[42:45], v[38:41], v[0:15]
	v_fmac_f32_e32 v34, v107, v32
	s_cbranch_scc1 .LBB0_243
	v_div_scale_f32 v32, s[0:1], v34, v34, 1.0
	v_rcp_f32_e32 v33, v32
	v_div_scale_f32 v35, vcc, 1.0, v34, 1.0
	v_readlane_b32 s0, v254, 43
	v_fma_f32 v36, -v32, v33, 1.0
	v_fmac_f32_e32 v33, v36, v33
	v_mul_f32_e32 v36, v35, v33
	v_fma_f32 v37, -v32, v36, v35
	v_fmac_f32_e32 v36, v37, v33
	v_fma_f32 v32, -v32, v36, v35
	v_div_fmas_f32 v32, v32, v33, v36
	v_div_fixup_f32 v32, v32, v34, 1.0
	v_lshlrev_b64 v[34:35], 11, v[96:97]
	v_readlane_b32 s1, v254, 44
	s_lshl_b32 s92, s4, 1
	v_pk_mul_f32 v[16:17], v[16:17], v[32:33] op_sel_hi:[1,0]
	v_lshl_add_u64 v[34:35], s[0:1], 0, v[34:35]
	v_lshl_add_u64 v[34:35], v[34:35], 0, s[92:93]
	v_pk_mul_f32 v[18:19], v[18:19], v[32:33] op_sel_hi:[1,0]
	v_lshlrev_b32_e32 v128, 3, v100
	v_cvt_pk_bf16_f32 v16, v16, v17
	v_cvt_pk_bf16_f32 v17, v18, v19
	v_lshl_add_u64 v[18:19], v[34:35], 0, v[128:129]
	s_mov_b64 s[0:1], 0x153ca200
	v_lshl_add_u64 v[34:35], v[18:19], 0, s[0:1]
	s_mov_b32 s0, 0x153ca000
	v_add_co_u32_e32 v18, vcc, s0, v18
	v_pk_mul_f32 v[0:1], v[0:1], v[32:33] op_sel_hi:[1,0]
	v_pk_mul_f32 v[2:3], v[2:3], v[32:33] op_sel_hi:[1,0]
	v_addc_co_u32_e32 v19, vcc, 0, v19, vcc
	v_cvt_pk_bf16_f32 v0, v0, v1
	v_cvt_pk_bf16_f32 v1, v2, v3
	global_store_dwordx2 v[18:19], v[16:17], off offset:512
	v_pk_mul_f32 v[16:17], v[20:21], v[32:33] op_sel_hi:[1,0]
	v_pk_mul_f32 v[18:19], v[22:23], v[32:33] op_sel_hi:[1,0]
	global_store_dwordx2 v[34:35], v[0:1], off offset:64
	v_pk_mul_f32 v[0:1], v[4:5], v[32:33] op_sel_hi:[1,0]
	v_pk_mul_f32 v[2:3], v[6:7], v[32:33] op_sel_hi:[1,0]
	v_cvt_pk_bf16_f32 v16, v16, v17
	v_cvt_pk_bf16_f32 v17, v18, v19
	v_cvt_pk_bf16_f32 v0, v0, v1
	v_cvt_pk_bf16_f32 v1, v2, v3
	global_store_dwordx2 v[34:35], v[16:17], off offset:16
	v_pk_mul_f32 v[16:17], v[24:25], v[32:33] op_sel_hi:[1,0]
	v_pk_mul_f32 v[18:19], v[26:27], v[32:33] op_sel_hi:[1,0]
	global_store_dwordx2 v[34:35], v[0:1], off offset:80
	v_pk_mul_f32 v[0:1], v[8:9], v[32:33] op_sel_hi:[1,0]
	v_pk_mul_f32 v[2:3], v[10:11], v[32:33] op_sel_hi:[1,0]
	v_cvt_pk_bf16_f32 v16, v16, v17
	v_cvt_pk_bf16_f32 v17, v18, v19
	v_cvt_pk_bf16_f32 v0, v0, v1
	v_cvt_pk_bf16_f32 v1, v2, v3
	global_store_dwordx2 v[34:35], v[16:17], off offset:32
	v_pk_mul_f32 v[16:17], v[28:29], v[32:33] op_sel_hi:[1,0]
	v_pk_mul_f32 v[18:19], v[30:31], v[32:33] op_sel_hi:[1,0]
	global_store_dwordx2 v[34:35], v[0:1], off offset:96
	v_pk_mul_f32 v[0:1], v[12:13], v[32:33] op_sel_hi:[1,0]
	v_pk_mul_f32 v[2:3], v[14:15], v[32:33] op_sel_hi:[1,0]
	v_cvt_pk_bf16_f32 v16, v16, v17
	v_cvt_pk_bf16_f32 v17, v18, v19
	v_cvt_pk_bf16_f32 v0, v0, v1
	v_cvt_pk_bf16_f32 v1, v2, v3
	global_store_dwordx2 v[34:35], v[16:17], off offset:48
	global_store_dwordx2 v[34:35], v[0:1], off offset:112
	s_barrier

.LBB0_270:
	s_barrier
	ds_write_b128 v126, v[32:35]
	ds_write_b128 v127, v[44:47]
	v_and_b32_e32 v223, 0xff, v160
	v_lshrrev_b32_e32 v224, 2, v223
	v_and_b32_e32 v225, 3, v223
	v_lshrrev_b32_e32 v226, 1, v225
	v_bfe_u32 v227, v224, 1, 1
	v_xor_b32_e32 v226, v226, v227
	v_lshlrev_b32_e32 v226, 6, v226
	v_and_b32_e32 v225, 1, v225
	v_lshl_or_b32 v226, v225, 5, v226
	v_lshl_add_u32 v226, v224, 7, v226
	v_add_u32_e32 v223, s78, v226
	v_and_b32_e32 v226, 63, v160
	v_lshrrev_b32_e32 v224, 5, v226
	v_bfe_u32 v227, v226, 2, 2
	v_lshl_add_u32 v224, v224, 2, v227
	v_lshlrev_b32_e32 v224, 7, v224
	v_bfe_u32 v227, v226, 3, 1
	v_lshl_or_b32 v224, v227, 6, v224
	v_bfe_u32 v227, v226, 4, 1
	v_lshl_or_b32 v224, v227, 5, v224
	v_and_b32_e32 v227, 3, v226
	v_lshl_or_b32 v224, v227, 3, v224
	v_add_u32_e32 v224, s78, v224
	v_xor_b32_e32 v225, 64, v224
	ds_write_b128 v223, v[40:43] offset:8192
	ds_write_b128 v223, v[36:39] offset:8208
	s_waitcnt lgkmcnt(0)
	s_barrier
	ds_read_b128 v[32:35], v138
	ds_read_b128 v[36:39], v138 offset:4096
	s_waitcnt lgkmcnt(1)
	v_mfma_f32_32x32x16_bf16 v[48:63], v[32:35], v[64:67], 0
	ds_read_b128 v[146:149], v139
	ds_read_b128 v[150:153], v139 offset:4096
	s_add_i32 s40, s33, s44
	v_cmp_ge_u32_e32 vcc, s40, v115
	v_cmp_lt_u32_e64 s[40:41], s40, v120
	s_and_b64 s[96:97], vcc, s[40:41]
	s_andn2_b64 vcc, exec, s[4:5]
	s_waitcnt lgkmcnt(2)
	v_mfma_f32_32x32x16_bf16 v[32:47], v[36:39], v[64:67], 0
	s_waitcnt lgkmcnt(1)
	v_mfma_f32_32x32x16_bf16 v[48:63], v[146:149], v[68:71], v[48:63]
	s_waitcnt lgkmcnt(0)
	v_mfma_f32_32x32x16_bf16 v[32:47], v[150:153], v[68:71], v[32:47]
	ds_read_b128 v[146:149], v140
	ds_read_b128 v[150:153], v140 offset:4096
	s_waitcnt lgkmcnt(1)
	v_mfma_f32_32x32x16_bf16 v[48:63], v[146:149], v[72:75], v[48:63]
	s_waitcnt lgkmcnt(0)
	v_mfma_f32_32x32x16_bf16 v[32:47], v[150:153], v[72:75], v[32:47]
	ds_read_b128 v[146:149], v141
	ds_read_b128 v[150:153], v141 offset:4096
	s_waitcnt lgkmcnt(1)
	v_mfma_f32_32x32x16_bf16 v[48:63], v[146:149], v[76:79], v[48:63]
	s_waitcnt lgkmcnt(0)
	v_mfma_f32_32x32x16_bf16 v[32:47], v[150:153], v[76:79], v[32:47]
	s_nop 9
	v_mul_f32_e32 v147, 0x3e000000, v48
	v_cndmask_b32_e64 v48, 0, 1, s[4:5]
	v_cmp_ne_u32_e64 s[40:41], 1, v48
	s_cbranch_vccnz .Lnat_np
	v_lshl_add_u32 v222, v124, 2, s78
	ds_read_b32 v190, v222 offset:16660
	ds_read_b32 v191, v222 offset:16668
	ds_read_b32 v192, v222 offset:16692
	ds_read_b32 v193, v222 offset:16700
	ds_read_b32 v194, v222 offset:16724
	ds_read_b32 v195, v222 offset:16732
	ds_read_b32 v196, v222 offset:16756
	ds_read_b32 v197, v222 offset:16764
	ds_read_b32 v198, v222 offset:16788
	ds_read_b32 v199, v222 offset:16796
	ds_read_b32 v200, v222 offset:16820
	ds_read_b32 v201, v222 offset:16828
	ds_read_b32 v202, v222 offset:16852
	ds_read_b32 v203, v222 offset:16860
	ds_read_b32 v204, v222 offset:16884
	ds_read_b32 v205, v222 offset:16892
	ds_read_b32 v206, v222 offset:16664
	ds_read_b32 v207, v222 offset:16672
	ds_read_b32 v208, v222 offset:16696
	ds_read_b32 v209, v222 offset:16704
	ds_read_b32 v210, v222 offset:16728
	ds_read_b32 v211, v222 offset:16736
	ds_read_b32 v212, v222 offset:16760
	ds_read_b32 v213, v222 offset:16768
	ds_read_b32 v214, v222 offset:16792
	ds_read_b32 v215, v222 offset:16800
	ds_read_b32 v216, v222 offset:16824
	ds_read_b32 v217, v222 offset:16832
	ds_read_b32 v218, v222 offset:16856
	ds_read_b32 v219, v222 offset:16864
	ds_read_b32 v220, v222 offset:16888
	ds_read_b32 v221, v222 offset:16896
	s_waitcnt lgkmcnt(0)
	s_and_b64 vcc, s[96:97], s[64:65]
	v_add_f32_e32 v48, v147, v190
	v_cndmask_b32_e32 v147, v169, v48, vcc
	v_mul_f32_e32 v146, 0x3e000000, v49
	s_and_b64 vcc, s[96:97], s[66:67]
	v_add_f32_e32 v48, v146, v206
	v_cndmask_b32_e32 v146, v169, v48, vcc
	v_mul_f32_e32 v119, 0x3e000000, v50
	s_and_b64 vcc, s[96:97], s[68:69]
	v_add_f32_e32 v48, v119, v191
	v_cndmask_b32_e32 v119, v169, v48, vcc
	v_mul_f32_e32 v145, 0x3e000000, v51
	s_and_b64 vcc, s[96:97], s[70:71]
	v_add_f32_e32 v48, v145, v207
	v_cndmask_b32_e32 v145, v169, v48, vcc
	v_mul_f32_e32 v51, 0x3e000000, v52
	s_and_b64 vcc, s[96:97], s[72:73]
	v_add_f32_e32 v48, v51, v192
	v_cndmask_b32_e32 v51, v169, v48, vcc
	v_mul_f32_e32 v52, 0x3e000000, v53
	s_and_b64 vcc, s[96:97], s[74:75]
	v_add_f32_e32 v48, v52, v208
	v_cndmask_b32_e32 v52, v169, v48, vcc
	v_mul_f32_e32 v48, 0x3e000000, v54
	v_readlane_b32 s4, v254, 45
	v_readlane_b32 s5, v254, 46
	s_and_b64 vcc, s[96:97], s[4:5]
	v_add_f32_e32 v48, v48, v193
	v_cndmask_b32_e32 v48, v169, v48, vcc
	v_mul_f32_e32 v50, 0x3e000000, v55
	v_readlane_b32 s4, v254, 47
	v_readlane_b32 s5, v254, 48
	s_and_b64 vcc, s[96:97], s[4:5]
	v_add_f32_e32 v49, v50, v209
	v_cndmask_b32_e32 v50, v169, v49, vcc
	v_mul_f32_e32 v49, 0x3e000000, v56
	v_readlane_b32 s4, v254, 49
	v_readlane_b32 s5, v254, 50
	v_readlane_b32 vcc_lo, v254, 51
	s_and_b64 s[4:5], s[96:97], s[4:5]
	v_readlane_b32 vcc_hi, v254, 52
	s_and_b64 vcc, s[4:5], vcc
	v_add_f32_e32 v49, v49, v194
	v_cndmask_b32_e32 v49, v169, v49, vcc
	v_mul_f32_e32 v53, 0x3e000000, v57
	v_readlane_b32 s4, v254, 53
	v_readlane_b32 s5, v254, 54
	v_readlane_b32 vcc_lo, v254, 55
	s_and_b64 s[4:5], s[96:97], s[4:5]
	v_readlane_b32 vcc_hi, v254, 56
	s_and_b64 vcc, s[4:5], vcc
	v_add_f32_e32 v53, v53, v210
	v_cndmask_b32_e32 v53, v169, v53, vcc
	v_mul_f32_e32 v54, 0x3e000000, v58
	v_readlane_b32 s4, v254, 57
	v_readlane_b32 s5, v254, 58
	v_readlane_b32 vcc_lo, v255, 26
	s_and_b64 s[4:5], s[96:97], s[4:5]
	v_readlane_b32 vcc_hi, v255, 27
	s_and_b64 vcc, s[4:5], vcc
	v_add_f32_e32 v54, v54, v195
	v_cndmask_b32_e32 v54, v169, v54, vcc
	v_mul_f32_e32 v55, 0x3e000000, v59
	v_readlane_b32 s4, v255, 28
	v_readlane_b32 s5, v255, 29
	v_readlane_b32 vcc_lo, v255, 30
	s_and_b64 s[4:5], s[96:97], s[4:5]
	v_readlane_b32 vcc_hi, v255, 31
	s_and_b64 vcc, s[4:5], vcc
	v_add_f32_e32 v55, v55, v211
	v_cndmask_b32_e32 v55, v169, v55, vcc
	v_mul_f32_e32 v56, 0x3e000000, v60
	v_readlane_b32 s4, v255, 32
	v_readlane_b32 s5, v255, 33
	v_readlane_b32 vcc_lo, v255, 34
	s_and_b64 s[4:5], s[96:97], s[4:5]
	v_readlane_b32 vcc_hi, v255, 35
	s_and_b64 vcc, s[4:5], vcc
	v_add_f32_e32 v56, v56, v196
	v_cndmask_b32_e32 v56, v169, v56, vcc
	v_mul_f32_e32 v57, 0x3e000000, v61
	v_readlane_b32 s4, v255, 36
	v_readlane_b32 s5, v255, 37
	v_readlane_b32 vcc_lo, v255, 38
	s_and_b64 s[4:5], s[96:97], s[4:5]
	v_readlane_b32 vcc_hi, v255, 39
	s_and_b64 vcc, s[4:5], vcc
	v_add_f32_e32 v57, v57, v212
	v_cndmask_b32_e32 v57, v169, v57, vcc
	v_mul_f32_e32 v58, 0x3e000000, v62
	v_readlane_b32 s4, v255, 40
	v_readlane_b32 s5, v255, 41
	v_readlane_b32 vcc_lo, v255, 42
	s_and_b64 s[4:5], s[96:97], s[4:5]
	v_readlane_b32 vcc_hi, v255, 43
	s_and_b64 vcc, s[4:5], vcc
	v_add_f32_e32 v58, v58, v197
	v_cndmask_b32_e32 v58, v169, v58, vcc
	v_mul_f32_e32 v59, 0x3e000000, v63
	v_readlane_b32 s4, v255, 44
	v_readlane_b32 s5, v255, 45
	v_readlane_b32 vcc_lo, v255, 46
	s_and_b64 s[4:5], s[96:97], s[4:5]
	v_readlane_b32 vcc_hi, v255, 47
	s_and_b64 vcc, s[4:5], vcc
	v_add_f32_e32 v59, v59, v213
	v_cndmask_b32_e32 v59, v169, v59, vcc
	v_mul_f32_e32 v60, 0x3e000000, v32
	v_readlane_b32 s4, v255, 48
	v_readlane_b32 s5, v255, 49
	v_readlane_b32 vcc_lo, v255, 50
	s_and_b64 s[4:5], s[96:97], s[4:5]
	v_readlane_b32 vcc_hi, v255, 51
	s_and_b64 vcc, s[4:5], vcc
	v_add_f32_e32 v32, v60, v198
	v_cndmask_b32_e32 v60, v169, v32, vcc
	v_mul_f32_e32 v61, 0x3e000000, v33
	v_readlane_b32 s4, v255, 52
	v_readlane_b32 s5, v255, 53
	v_readlane_b32 vcc_lo, v255, 54
	s_and_b64 s[4:5], s[96:97], s[4:5]
	v_readlane_b32 vcc_hi, v255, 55
	s_and_b64 vcc, s[4:5], vcc
	v_add_f32_e32 v32, v61, v214
	v_cndmask_b32_e32 v61, v169, v32, vcc
	v_mul_f32_e32 v62, 0x3e000000, v34
	v_readlane_b32 s4, v255, 56
	v_readlane_b32 s5, v255, 57
	v_readlane_b32 vcc_lo, v255, 58
	s_and_b64 s[4:5], s[96:97], s[4:5]
	v_readlane_b32 vcc_hi, v255, 59
	s_and_b64 vcc, s[4:5], vcc
	v_add_f32_e32 v32, v62, v199
	v_cndmask_b32_e32 v62, v169, v32, vcc
	v_mul_f32_e32 v150, 0x3e000000, v35
	v_readlane_b32 s4, v255, 60
	v_readlane_b32 s5, v255, 61
	v_readlane_b32 vcc_lo, v255, 62
	s_and_b64 s[4:5], s[96:97], s[4:5]
	v_readlane_b32 vcc_hi, v255, 63
	s_and_b64 vcc, s[4:5], vcc
	v_add_f32_e32 v32, v150, v215
	v_cndmask_b32_e32 v150, v169, v32, vcc
	v_mul_f32_e32 v151, 0x3e000000, v36
	s_and_b64 s[4:5], s[96:97], s[6:7]
	s_and_b64 vcc, s[4:5], s[8:9]
	v_add_f32_e32 v32, v151, v200
	v_cndmask_b32_e32 v151, v169, v32, vcc
	v_mul_f32_e32 v153, 0x3e000000, v37
	s_and_b64 s[4:5], s[96:97], s[10:11]
	s_and_b64 vcc, s[4:5], s[12:13]
	v_add_f32_e32 v32, v153, v216
	v_cndmask_b32_e32 v153, v169, v32, vcc
	v_mul_f32_e32 v149, 0x3e000000, v38
	s_and_b64 s[4:5], s[96:97], s[14:15]
	s_and_b64 vcc, s[4:5], s[16:17]
	v_add_f32_e32 v32, v149, v201
	v_cndmask_b32_e32 v149, v169, v32, vcc
	v_mul_f32_e32 v152, 0x3e000000, v39
	s_and_b64 s[4:5], s[96:97], s[18:19]
	s_and_b64 vcc, s[4:5], s[20:21]
	v_add_f32_e32 v32, v152, v217
	v_cndmask_b32_e32 v152, v169, v32, vcc
	v_mul_f32_e32 v63, 0x3e000000, v40
	s_and_b64 vcc, s[96:97], s[22:23]
	v_add_f32_e32 v32, v63, v202
	v_cndmask_b32_e32 v63, v169, v32, vcc
	v_mul_f32_e32 v148, 0x3e000000, v41
	s_and_b64 vcc, s[96:97], s[24:25]
	v_add_f32_e32 v32, v148, v218
	v_cndmask_b32_e32 v148, v169, v32, vcc
	v_mul_f32_e32 v41, 0x3e000000, v42
	s_and_b64 vcc, s[96:97], s[26:27]
	v_add_f32_e32 v32, v41, v203
	v_cndmask_b32_e32 v41, v169, v32, vcc
	v_mul_f32_e32 v42, 0x3e000000, v43
	s_and_b64 vcc, s[96:97], s[28:29]
	v_add_f32_e32 v32, v42, v219
	v_cndmask_b32_e32 v42, v169, v32, vcc
	v_mul_f32_e32 v39, 0x3e000000, v44
	s_and_b64 vcc, s[96:97], s[30:31]
	v_add_f32_e32 v32, v39, v204
	v_cndmask_b32_e32 v39, v169, v32, vcc
	v_mul_f32_e32 v45, 0x3e000000, v45
	s_and_b64 vcc, s[96:97], s[34:35]
	v_add_f32_e32 v32, v45, v220
	v_cndmask_b32_e32 v45, v169, v32, vcc
	v_mul_f32_e32 v46, 0x3e000000, v46
	s_and_b64 vcc, s[96:97], s[0:1]
	v_add_f32_e32 v32, v46, v205
	v_cndmask_b32_e32 v46, v169, v32, vcc
	v_mul_f32_e32 v154, 0x3e000000, v47
	s_and_b64 vcc, s[96:97], s[38:39]
	v_add_f32_e32 v32, v154, v221
	v_cndmask_b32_e32 v154, v169, v32, vcc
	s_branch .LBB0_334

.LBB0_334:
	s_mov_b32 s4, 0xf149f2ca
	v_max3_f32 v32, v147, s4, v146
	v_max3_f32 v32, v32, v119, v145
	v_max3_f32 v32, v32, v51, v52
	v_max3_f32 v32, v32, v48, v50
	v_max3_f32 v32, v32, v49, v53
	v_max3_f32 v32, v32, v54, v55
	v_max3_f32 v32, v32, v56, v57
	v_max3_f32 v32, v32, v58, v59
	v_max3_f32 v32, v32, v60, v61
	v_max3_f32 v32, v32, v62, v150
	v_max3_f32 v32, v32, v151, v153
	v_max3_f32 v32, v32, v149, v152
	v_max3_f32 v32, v32, v63, v148
	v_max3_f32 v32, v32, v41, v42
	v_max3_f32 v32, v32, v39, v45
	v_max3_f32 v32, v32, v46, v154
	ds_bpermute_b32 v33, v121, v32
	v_cmp_lt_f32_e32 vcc, s86, v147
	s_add_i32 s44, s44, 1
	s_movk_i32 s96, 0x101
	v_add_u32_e32 v118, 64, v118
	s_waitcnt lgkmcnt(0)
	v_max3_f32 v33, v144, v32, v33
	v_sub_f32_e32 v34, v147, v33
	v_mul_f32_e32 v34, 0x3fb8aa3b, v34
	v_sub_f32_e32 v36, v146, v33
	v_exp_f32_e32 v34, v34
	v_mul_f32_e32 v36, 0x3fb8aa3b, v36
	v_exp_f32_e32 v36, v36
	v_sub_f32_e32 v32, v144, v33
	v_cndmask_b32_e32 v35, 0, v34, vcc
	v_cmp_lt_f32_e32 vcc, s86, v146
	v_add_f32_e32 v34, 0, v35
	v_mul_f32_e32 v32, 0x3fb8aa3b, v32
	v_cndmask_b32_e32 v38, 0, v36, vcc
	v_sub_f32_e32 v36, v119, v33
	v_mul_f32_e32 v36, 0x3fb8aa3b, v36
	v_exp_f32_e32 v36, v36
	v_cmp_lt_f32_e32 vcc, s86, v119
	v_add_f32_e32 v34, v38, v34
	v_exp_f32_e32 v32, v32
	v_cndmask_b32_e32 v43, 0, v36, vcc
	v_sub_f32_e32 v36, v145, v33
	v_mul_f32_e32 v36, 0x3fb8aa3b, v36
	v_exp_f32_e32 v36, v36
	v_cmp_lt_f32_e32 vcc, s86, v145
	v_add_f32_e32 v34, v43, v34
	v_cvt_pk_bf16_f32 v146, v35, v38
	v_cndmask_b32_e32 v47, 0, v36, vcc
	v_sub_f32_e32 v36, v51, v33
	v_mul_f32_e32 v36, 0x3fb8aa3b, v36
	v_exp_f32_e32 v36, v36
	v_cmp_lt_f32_e32 vcc, s86, v51
	v_add_f32_e32 v34, v47, v34
	v_add_u32_e32 v38, 0x2000, v142
	v_cndmask_b32_e32 v51, 0, v36, vcc
	v_sub_f32_e32 v36, v52, v33
	v_mul_f32_e32 v36, 0x3fb8aa3b, v36
	v_exp_f32_e32 v36, v36
	v_cmp_lt_f32_e32 vcc, s86, v52
	v_add_f32_e32 v34, v51, v34
	v_pk_mul_f32 v[30:31], v[30:31], v[32:33] op_sel_hi:[1,0]
	v_cndmask_b32_e32 v52, 0, v36, vcc
	v_sub_f32_e32 v36, v48, v33
	v_mul_f32_e32 v36, 0x3fb8aa3b, v36
	v_exp_f32_e32 v36, v36
	v_cmp_lt_f32_e32 vcc, s86, v48
	v_add_f32_e32 v34, v52, v34
	v_pk_mul_f32 v[28:29], v[28:29], v[32:33] op_sel_hi:[1,0]
	v_cndmask_b32_e32 v119, 0, v36, vcc
	v_sub_f32_e32 v36, v50, v33
	v_mul_f32_e32 v36, 0x3fb8aa3b, v36
	v_exp_f32_e32 v36, v36
	v_cmp_lt_f32_e32 vcc, s86, v50
	v_add_f32_e32 v34, v119, v34
	v_pk_mul_f32 v[26:27], v[26:27], v[32:33] op_sel_hi:[1,0]
	v_cndmask_b32_e32 v144, 0, v36, vcc
	v_add_f32_e32 v36, v144, v34
	v_sub_f32_e32 v34, v49, v33
	v_mul_f32_e32 v34, 0x3fb8aa3b, v34
	v_exp_f32_e32 v34, v34
	v_cmp_lt_f32_e32 vcc, s86, v49
	v_pk_mul_f32 v[24:25], v[24:25], v[32:33] op_sel_hi:[1,0]
	v_pk_mul_f32 v[22:23], v[22:23], v[32:33] op_sel_hi:[1,0]
	v_cndmask_b32_e32 v34, 0, v34, vcc
	v_add_f32_e32 v37, v34, v36
	v_sub_f32_e32 v36, v53, v33
	v_mul_f32_e32 v36, 0x3fb8aa3b, v36
	v_exp_f32_e32 v36, v36
	v_cmp_lt_f32_e32 vcc, s86, v53
	v_sub_f32_e32 v53, v59, v33
	v_mul_f32_e32 v53, 0x3fb8aa3b, v53
	v_cndmask_b32_e32 v36, 0, v36, vcc
	v_add_f32_e32 v40, v36, v37
	v_sub_f32_e32 v37, v54, v33
	v_mul_f32_e32 v37, 0x3fb8aa3b, v37
	v_exp_f32_e32 v37, v37
	v_cmp_lt_f32_e32 vcc, s86, v54
	v_exp_f32_e32 v53, v53
	v_pk_mul_f32 v[20:21], v[20:21], v[32:33] op_sel_hi:[1,0]
	v_cndmask_b32_e32 v37, 0, v37, vcc
	v_add_f32_e32 v44, v37, v40
	v_sub_f32_e32 v40, v55, v33
	v_mul_f32_e32 v40, 0x3fb8aa3b, v40
	v_exp_f32_e32 v40, v40
	v_cmp_lt_f32_e32 vcc, s86, v55
	v_pk_mul_f32 v[18:19], v[18:19], v[32:33] op_sel_hi:[1,0]
	v_pk_mul_f32 v[16:17], v[16:17], v[32:33] op_sel_hi:[1,0]
	v_cndmask_b32_e32 v40, 0, v40, vcc
	v_add_f32_e32 v48, v40, v44
	v_sub_f32_e32 v44, v56, v33
	v_mul_f32_e32 v44, 0x3fb8aa3b, v44
	v_exp_f32_e32 v44, v44
	v_cmp_lt_f32_e32 vcc, s86, v56
	v_cvt_pk_bf16_f32 v147, v43, v47
	v_add_u32_e32 v47, 0x3000, v142
	v_cndmask_b32_e32 v44, 0, v44, vcc
	v_add_f32_e32 v49, v44, v48
	v_sub_f32_e32 v48, v57, v33
	v_mul_f32_e32 v48, 0x3fb8aa3b, v48
	v_exp_f32_e32 v48, v48
	v_cmp_lt_f32_e32 vcc, s86, v57
	v_sub_f32_e32 v57, v150, v33
	v_mul_f32_e32 v57, 0x3fb8aa3b, v57
	v_cndmask_b32_e32 v48, 0, v48, vcc
	v_add_f32_e32 v50, v48, v49
	v_sub_f32_e32 v49, v58, v33
	v_mul_f32_e32 v49, 0x3fb8aa3b, v49
	v_exp_f32_e32 v49, v49
	v_cmp_lt_f32_e32 vcc, s86, v58
	v_sub_f32_e32 v58, v151, v33
	v_exp_f32_e32 v57, v57
	v_cndmask_b32_e32 v49, 0, v49, vcc
	v_cmp_lt_f32_e32 vcc, s86, v59
	v_add_f32_e32 v50, v49, v50
	v_mul_f32_e32 v58, 0x3fb8aa3b, v58
	v_cndmask_b32_e32 v53, 0, v53, vcc
	v_add_f32_e32 v54, v53, v50
	v_sub_f32_e32 v50, v60, v33
	v_mul_f32_e32 v50, 0x3fb8aa3b, v50
	v_exp_f32_e32 v50, v50
	v_cmp_lt_f32_e32 vcc, s86, v60
	v_sub_f32_e32 v59, v153, v33
	v_exp_f32_e32 v58, v58
	v_cndmask_b32_e32 v50, 0, v50, vcc
	v_add_f32_e32 v55, v50, v54
	v_sub_f32_e32 v54, v61, v33
	v_mul_f32_e32 v54, 0x3fb8aa3b, v54
	v_exp_f32_e32 v54, v54
	v_cmp_lt_f32_e32 vcc, s86, v61
	v_mul_f32_e32 v59, 0x3fb8aa3b, v59
	v_exp_f32_e32 v59, v59
	v_cndmask_b32_e32 v54, 0, v54, vcc
	v_add_f32_e32 v56, v54, v55
	v_sub_f32_e32 v55, v62, v33
	v_mul_f32_e32 v55, 0x3fb8aa3b, v55
	v_exp_f32_e32 v55, v55
	v_cmp_lt_f32_e32 vcc, s86, v62
	v_pk_mul_f32 v[14:15], v[14:15], v[32:33] op_sel_hi:[1,0]
	v_pk_mul_f32 v[12:13], v[12:13], v[32:33] op_sel_hi:[1,0]
	v_cndmask_b32_e32 v55, 0, v55, vcc
	v_cmp_lt_f32_e32 vcc, s86, v150
	v_add_f32_e32 v56, v55, v56
	v_pk_mul_f32 v[10:11], v[10:11], v[32:33] op_sel_hi:[1,0]
	v_cndmask_b32_e32 v57, 0, v57, vcc
	v_cmp_lt_f32_e32 vcc, s86, v151
	v_add_f32_e32 v56, v57, v56
	v_pk_mul_f32 v[8:9], v[8:9], v[32:33] op_sel_hi:[1,0]
	v_cndmask_b32_e32 v58, 0, v58, vcc
	v_cmp_lt_f32_e32 vcc, s86, v153
	v_add_f32_e32 v56, v58, v56
	v_pk_mul_f32 v[6:7], v[6:7], v[32:33] op_sel_hi:[1,0]
	v_cndmask_b32_e32 v60, 0, v59, vcc
	v_sub_f32_e32 v59, v149, v33
	v_mul_f32_e32 v59, 0x3fb8aa3b, v59
	v_exp_f32_e32 v59, v59
	v_cmp_lt_f32_e32 vcc, s86, v149
	v_add_f32_e32 v56, v60, v56
	v_cvt_pk_bf16_f32 v149, v119, v144
	v_cndmask_b32_e32 v61, 0, v59, vcc
	v_sub_f32_e32 v59, v152, v33
	v_mul_f32_e32 v59, 0x3fb8aa3b, v59
	v_exp_f32_e32 v59, v59
	v_cmp_lt_f32_e32 vcc, s86, v152
	v_add_f32_e32 v56, v61, v56
	v_pk_mul_f32 v[4:5], v[4:5], v[32:33] op_sel_hi:[1,0]
	v_cndmask_b32_e32 v62, 0, v59, vcc
	v_add_f32_e32 v59, v62, v56
	v_sub_f32_e32 v56, v63, v33
	v_mul_f32_e32 v56, 0x3fb8aa3b, v56
	v_exp_f32_e32 v56, v56
	v_cmp_lt_f32_e32 vcc, s86, v63
	v_pk_mul_f32 v[2:3], v[2:3], v[32:33] op_sel_hi:[1,0]
	v_pk_mul_f32 v[0:1], v[0:1], v[32:33] op_sel_hi:[1,0]
	v_cndmask_b32_e32 v56, 0, v56, vcc
	v_add_f32_e32 v63, v56, v59
	v_sub_f32_e32 v59, v148, v33
	v_mul_f32_e32 v59, 0x3fb8aa3b, v59
	v_exp_f32_e32 v59, v59
	v_cmp_lt_f32_e32 vcc, s86, v148
	v_cvt_pk_bf16_f32 v148, v51, v52
	v_cvt_pk_bf16_f32 v34, v34, v36
	v_cndmask_b32_e32 v59, 0, v59, vcc
	v_cmp_lt_f32_e32 vcc, s86, v41
	v_sub_f32_e32 v41, v41, v33
	v_mul_f32_e32 v41, 0x3fb8aa3b, v41
	v_exp_f32_e32 v41, v41
	v_add_f32_e32 v63, v59, v63
	v_cvt_pk_bf16_f32 v36, v44, v48
	v_cvt_pk_bf16_f32 v35, v37, v40
	v_cndmask_b32_e32 v41, 0, v41, vcc
	v_cmp_lt_f32_e32 vcc, s86, v42
	v_sub_f32_e32 v42, v42, v33
	v_mul_f32_e32 v42, 0x3fb8aa3b, v42
	v_exp_f32_e32 v42, v42
	v_add_f32_e32 v63, v41, v63
	v_cvt_pk_bf16_f32 v37, v49, v53
	v_add_u32_e32 v124, 31, v124
	v_cndmask_b32_e32 v134, 0, v42, vcc
	v_cmp_lt_f32_e32 vcc, s86, v39
	v_sub_f32_e32 v39, v39, v33
	v_mul_f32_e32 v39, 0x3fb8aa3b, v39
	v_exp_f32_e32 v39, v39
	v_add_f32_e32 v42, v134, v63
	v_add_u32_e32 v125, 64, v125
	s_cmp_lg_u32 s46, s44
	v_cndmask_b32_e32 v63, 0, v39, vcc
	v_add_f32_e32 v39, v63, v42
	v_sub_f32_e32 v42, v45, v33
	v_mul_f32_e32 v42, 0x3fb8aa3b, v42
	v_exp_f32_e32 v42, v42
	v_cmp_lt_f32_e32 vcc, s86, v45
	s_nop 1
	v_cndmask_b32_e32 v135, 0, v42, vcc
	v_sub_f32_e32 v42, v46, v33
	v_mul_f32_e32 v42, 0x3fb8aa3b, v42
	v_exp_f32_e32 v42, v42
	v_cmp_lt_f32_e32 vcc, s86, v46
	v_add_f32_e32 v39, v135, v39
	s_nop 0
	v_cndmask_b32_e32 v46, 0, v42, vcc
	v_sub_f32_e32 v42, v154, v33
	v_cmp_lt_f32_e32 vcc, s86, v154
	v_mul_f32_e32 v42, 0x3fb8aa3b, v42
	ds_read_b64_tr_b16 v[150:151], v224 offset:8192
	ds_read_b64_tr_b16 v[152:153], v224 offset:9216
	ds_read_b64_tr_b16 v[154:155], v224 offset:10240
	ds_read_b64_tr_b16 v[156:157], v224 offset:11264
	v_exp_f32_e32 v42, v42
	s_waitcnt lgkmcnt(2)
	v_mfma_f32_32x32x16_bf16 v[16:31], v[150:153], v[146:149], v[16:31]
	ds_read_b64_tr_b16 v[150:151], v225 offset:8192
	ds_read_b64_tr_b16 v[152:153], v225 offset:9216
	v_add_f32_e32 v39, v46, v39
	v_cndmask_b32_e32 v136, 0, v42, vcc
	v_add_f32_e32 v39, v136, v39
	ds_bpermute_b32 v42, v121, v39
	s_waitcnt lgkmcnt(0)
	v_add_f32_e32 v39, v39, v42
	ds_read_b64_tr_b16 v[42:43], v225 offset:10240
	ds_read_b64_tr_b16 v[44:45], v225 offset:11264
	v_mfma_f32_32x32x16_bf16 v[0:15], v[150:153], v[146:149], v[0:15]
	v_fmac_f32_e32 v39, v143, v32
	s_waitcnt lgkmcnt(0)
	v_mfma_f32_32x32x16_bf16 v[0:15], v[42:45], v[34:37], v[0:15]
	ds_read_b64_tr_b16 v[42:43], v224 offset:12288
	ds_read_b64_tr_b16 v[44:45], v224 offset:13312
	v_mfma_f32_32x32x16_bf16 v[16:31], v[154:157], v[34:37], v[16:31]
	v_cvt_pk_bf16_f32 v34, v50, v54
	v_cvt_pk_bf16_f32 v35, v55, v57
	v_cvt_pk_bf16_f32 v36, v58, v60
	v_cvt_pk_bf16_f32 v37, v61, v62
	s_waitcnt lgkmcnt(0)
	s_nop 0
	v_mfma_f32_32x32x16_bf16 v[16:31], v[42:45], v[34:37], v[16:31]
	ds_read_b64_tr_b16 v[42:43], v225 offset:12288
	ds_read_b64_tr_b16 v[44:45], v225 offset:13312
	s_waitcnt lgkmcnt(0)
	v_mfma_f32_32x32x16_bf16 v[0:15], v[42:45], v[34:37], v[0:15]
	v_cvt_pk_bf16_f32 v35, v41, v134
	ds_read_b64_tr_b16 v[40:41], v224 offset:14336
	ds_read_b64_tr_b16 v[42:43], v224 offset:15360
	v_cvt_pk_bf16_f32 v34, v56, v59
	v_cvt_pk_bf16_f32 v36, v63, v135
	v_cvt_pk_bf16_f32 v37, v46, v136
	s_waitcnt lgkmcnt(0)
	s_nop 0
	v_mfma_f32_32x32x16_bf16 v[16:31], v[40:43], v[34:37], v[16:31]
	ds_read_b64_tr_b16 v[40:41], v225 offset:14336
	ds_read_b64_tr_b16 v[42:43], v225 offset:15360
	s_waitcnt lgkmcnt(0)
	v_mfma_f32_32x32x16_bf16 v[0:15], v[40:43], v[34:37], v[0:15]
	s_cbranch_scc0 .LBB0_336
	v_mov_b32_e32 v144, v33
	v_mov_b32_e32 v143, v39
	s_branch .LBB0_262
